# prep waves trimmed: operand loads use SGPR-base addressing (no VALU address math), norm 1/max(sqrt(ss),1e-12) via v_rsq_f32 of max(ss,1e-24), late weight-transpose packs with v_cvt_pk_bf16_f32, redund
# speedup vs baseline: 1.0811x; 1.0021x over previous
.LBB0_950:
	s_or_b64 exec, exec, s[4:5]
	s_waitcnt lgkmcnt(1)
	v_add_f32_e32 v7, v11, v45
	v_mul_f32_e32 v11, 0x4f800000, v7
	v_cmp_gt_f32_e32 vcc, s28, v7
	v_add_u32_e32 v5, 0x3000, v5
	ds_write2_b64 v5, v[16:17], v[28:29] offset1:32
	v_cndmask_b32_e32 v7, v7, v11, vcc
	v_sqrt_f32_e32 v11, v7
	s_or_b32 s8, s8, 32
	s_movk_i32 s12, 0xf000
	v_mov_b32_e32 v45, 0
	v_add_u32_e32 v18, -1, v11
	v_fma_f32 v19, -v18, v11, v7
	v_cmp_ge_f32_e64 s[4:5], 0, v19
	v_add_u32_e32 v19, 1, v11
	s_add_i32 s30, s27, s6
	v_cndmask_b32_e64 v18, v11, v18, s[4:5]
	v_fma_f32 v11, -v19, v11, v7
	v_cmp_lt_f32_e64 s[4:5], 0, v11
	s_add_i32 s30, s30, -4
	v_lshrrev_b32_e32 v111, 3, v100
	v_cndmask_b32_e64 v11, v18, v19, s[4:5]
	v_mul_f32_e32 v18, 0x37800000, v11
	v_cndmask_b32_e32 v11, v11, v18, vcc
	v_cmp_class_f32_e32 vcc, v7, v103
	s_mov_b64 s[14:15], 0x10440000
	s_mov_b32 s17, s7
	v_cndmask_b32_e32 v7, v11, v7, vcc
	v_max_f32_e32 v7, 0x2b8cbccc, v7
	v_div_scale_f32 v11, s[4:5], v7, v7, 1.0
	v_rcp_f32_e32 v18, v11
	s_movk_i32 s5, 0x1000
	s_movk_i32 s4, 0x1a40
	s_mov_b64 s[18:19], 0x12520000
	v_fma_f32 v19, -v11, v18, 1.0
	v_fmac_f32_e32 v18, v19, v18
	v_div_scale_f32 v19, vcc, 1.0, v7, 1.0
	v_mul_f32_e32 v20, v19, v18
	v_fma_f32 v21, -v11, v20, v19
	v_fmac_f32_e32 v20, v21, v18
	v_fma_f32 v11, -v11, v20, v19
	v_div_fmas_f32 v11, v11, v18, v20
	v_div_fixup_f32 v18, v11, v7, 1.0
	v_pk_mul_f32 v[16:17], v[26:27], v[18:19] op_sel_hi:[1,0] neg_lo:[0,1] neg_hi:[0,1]
	v_mov_b32_e32 v7, v45
	v_pk_mul_f32 v[18:19], v[16:17], v[24:25] neg_lo:[1,0] neg_hi:[1,0]
	ds_write2_b64 v5, v[16:17], v[18:19] offset0:64 offset1:96
	ds_write2_b64 v5, v[22:23], v[30:31] offset0:128 offset1:160
	v_lshl_add_u64 v[16:17], s[8:9], 0, v[2:3]
	v_mul_hi_i32_i24_e32 v19, 0x1a40, v16
	v_mul_i32_i24_e32 v18, 0x1a40, v16
	v_lshl_add_u64 v[18:19], v[8:9], 0, v[18:19]
	v_add_co_u32_e32 v20, vcc, s5, v18
	v_lshlrev_b64 v[24:25], 12, v[16:17]
	s_nop 0
	v_addc_co_u32_e32 v21, vcc, 0, v19, vcc
	v_lshlrev_b64 v[16:17], 11, v[16:17]
	v_add_co_u32_e32 v22, vcc, s12, v18
	v_lshl_add_u64 v[16:17], v[14:15], 0, v[16:17]
	s_nop 0
	v_addc_co_u32_e32 v23, vcc, -1, v19, vcc
	v_lshl_add_u64 v[24:25], v[12:13], 0, v[24:25]
	global_load_dword v112, v[18:19], off
	global_load_dword v113, v[18:19], off offset:2048
	global_load_dword v114, v[20:21], off
	global_load_dword v115, v[22:23], off offset:-2624
	global_load_dword v116, v[22:23], off offset:-576
	global_load_dwordx2 v[48:49], v[24:25], off
	global_load_dword v120, v[16:17], off
	global_load_dword v119, v[18:19], off offset:-2624
	v_add_u32_e32 v16, s8, v6
	v_mad_u64_u32 v[18:19], s[10:11], v16, s4, v[8:9]
	v_mov_b32_e32 v17, v45
	v_add_co_u32_e32 v20, vcc, s5, v18
	v_lshlrev_b64 v[24:25], 12, v[16:17]
	s_nop 0
	v_addc_co_u32_e32 v21, vcc, 0, v19, vcc
	v_lshlrev_b64 v[16:17], 11, v[16:17]
	v_add_co_u32_e32 v22, vcc, s12, v18
	v_lshl_add_u64 v[16:17], v[14:15], 0, v[16:17]
	s_nop 0
	v_addc_co_u32_e32 v23, vcc, -1, v19, vcc
	v_lshl_add_u64 v[24:25], v[12:13], 0, v[24:25]
	global_load_dword v128, v[18:19], off
	global_load_dword v121, v[18:19], off offset:2048
	global_load_dword v129, v[20:21], off
	global_load_dword v122, v[22:23], off offset:-2624
	global_load_dword v123, v[22:23], off offset:-576
	global_load_dwordx2 v[50:51], v[24:25], off
	global_load_dword v125, v[16:17], off
	global_load_dword v124, v[18:19], off offset:-2624
	v_add_u32_e32 v16, s8, v44
	v_mad_u64_u32 v[18:19], s[10:11], v16, s4, v[8:9]
	v_mov_b32_e32 v17, v45
	v_add_co_u32_e32 v20, vcc, s5, v18
	v_lshlrev_b64 v[24:25], 12, v[16:17]
	s_nop 0
	v_addc_co_u32_e32 v21, vcc, 0, v19, vcc
	v_lshlrev_b64 v[16:17], 11, v[16:17]
	v_add_co_u32_e32 v22, vcc, s12, v18
	v_lshl_add_u64 v[16:17], v[14:15], 0, v[16:17]
	s_nop 0
	v_addc_co_u32_e32 v23, vcc, -1, v19, vcc
	v_lshl_add_u64 v[24:25], v[12:13], 0, v[24:25]
	global_load_dword v133, v[18:19], off
	global_load_dword v126, v[18:19], off offset:2048
	global_load_dword v134, v[20:21], off
	global_load_dword v127, v[22:23], off offset:-2624
	global_load_dword v130, v[22:23], off offset:-576
	global_load_dwordx2 v[74:75], v[24:25], off
	global_load_dword v132, v[16:17], off
	global_load_dword v131, v[18:19], off offset:-2624
	v_add_u32_e32 v16, s8, v10
	v_mad_u64_u32 v[8:9], s[8:9], v16, s4, v[8:9]
	v_add_co_u32_e32 v18, vcc, s5, v8
	v_mov_b32_e32 v17, v45
	s_nop 0
	v_addc_co_u32_e32 v19, vcc, 0, v9, vcc
	v_add_co_u32_e32 v20, vcc, s12, v8
	v_lshlrev_b64 v[22:23], 12, v[16:17]
	v_lshlrev_b64 v[16:17], 11, v[16:17]
	v_addc_co_u32_e32 v21, vcc, -1, v9, vcc
	v_lshl_add_u64 v[12:13], v[12:13], 0, v[22:23]
	v_lshl_add_u64 v[14:15], v[14:15], 0, v[16:17]
	global_load_dword v140, v[8:9], off
	global_load_dword v136, v[8:9], off offset:2048
	global_load_dword v141, v[18:19], off
	global_load_dword v137, v[20:21], off offset:-2624
	global_load_dword v138, v[20:21], off offset:-576
	global_load_dwordx2 v[88:89], v[12:13], off
	global_load_dword v142, v[14:15], off
	global_load_dword v139, v[8:9], off offset:-2624
	s_mul_i32 s5, s27, 0x2100
	s_add_i32 s5, s5, 0
	s_add_i32 s5, s5, 0xfc00
	s_add_u32 s10, s94, 0x4700000
	s_addc_u32 s11, s95, 0
	s_add_u32 s12, s94, 0x2700000
	s_addc_u32 s13, s95, 0
	s_add_u32 s8, s94, 0x1f00000
	s_addc_u32 s9, s95, 0
	s_lshl_b32 s6, s24, 24
	v_lshlrev_b64 v[12:13], 12, v[2:3]
	v_and_b32_e32 v5, 7, v166
	v_lshl_add_u64 v[12:13], s[6:7], 0, v[12:13]
	v_lshl_add_u32 v117, v5, 4, s5
	v_lshlrev_b32_e32 v46, 3, v5
	v_mul_u32_u24_e32 v5, 0x420, v5
	v_lshlrev_b32_e32 v8, 2, v111
	v_lshl_add_u64 v[12:13], v[12:13], 0, v[0:1]
	v_add3_u32 v106, s5, v5, v8
	v_lshlrev_b32_e32 v5, 2, v166
	v_lshl_add_u64 v[52:53], v[12:13], 0, s[14:15]
	v_lshlrev_b64 v[12:13], 11, v[2:3]
	v_mul_hi_i32_i24_e32 v3, 0x1a40, v2
	v_mul_i32_i24_e32 v2, 0x1a40, v2
	v_mov_b32_e32 v9, 0x1a40000
	v_and_b32_e32 v8, 28, v5
	v_mov_b32_e32 v5, v45
	v_mad_u64_u32 v[2:3], s[20:21], s24, v9, v[2:3]
	v_lshl_add_u64 v[56:57], v[2:3], 0, v[4:5]
	v_lshlrev_b64 v[2:3], 12, v[6:7]
	v_lshl_add_u64 v[2:3], s[6:7], 0, v[2:3]
	v_lshl_add_u64 v[2:3], v[2:3], 0, v[0:1]
	v_lshl_add_u64 v[58:59], v[2:3], 0, s[14:15]
	v_lshlrev_b64 v[2:3], 11, v[6:7]
	v_mad_u64_u32 v[6:7], s[20:21], v6, s4, 0
	v_mad_u64_u32 v[14:15], s[20:21], v44, s4, 0
	v_mov_b32_e32 v11, v45
	v_mad_u64_u32 v[6:7], s[20:21], s24, v9, v[6:7]
	v_mad_u64_u32 v[14:15], s[20:21], s24, v9, v[14:15]
	v_lshl_add_u64 v[62:63], v[6:7], 0, v[4:5]
	v_lshlrev_b64 v[6:7], 12, v[44:45]
	v_lshl_add_u64 v[68:69], v[14:15], 0, v[4:5]
	v_lshlrev_b64 v[14:15], 12, v[10:11]
	v_lshl_add_u64 v[6:7], s[6:7], 0, v[6:7]
	v_lshl_add_u64 v[14:15], s[6:7], 0, v[14:15]
	v_lshl_add_u64 v[6:7], v[6:7], 0, v[0:1]
	v_lshl_add_u64 v[0:1], v[14:15], 0, v[0:1]
	s_lshl_b32 s16, s24, 23
	v_lshl_add_u64 v[70:71], v[0:1], 0, s[14:15]
	v_lshlrev_b64 v[0:1], 11, v[10:11]
	v_lshl_add_u64 v[64:65], v[6:7], 0, s[14:15]
	v_lshlrev_b64 v[6:7], 11, v[44:45]
	v_lshl_add_u64 v[0:1], s[16:17], 0, v[0:1]
	v_lshl_add_u64 v[6:7], s[16:17], 0, v[6:7]
	v_lshl_add_u64 v[0:1], v[0:1], 0, v[4:5]
	v_lshl_add_u64 v[12:13], s[16:17], 0, v[12:13]
	v_lshl_add_u64 v[2:3], s[16:17], 0, v[2:3]
	v_lshl_add_u64 v[6:7], v[6:7], 0, v[4:5]
	v_lshl_add_u64 v[72:73], v[0:1], 0, s[18:19]
	v_mad_u64_u32 v[10:11], s[4:5], v10, s4, 0
	s_mov_b64 s[14:15], 0x10000
	v_lshl_add_u64 v[0:1], s[92:93], 0, v[0:1]
	v_lshl_add_u64 v[12:13], v[12:13], 0, v[4:5]
	v_lshl_add_u64 v[2:3], v[2:3], 0, v[4:5]
	v_mad_u64_u32 v[10:11], s[4:5], s24, v9, v[10:11]
	v_lshl_add_u64 v[80:81], v[0:1], 0, s[14:15]
	v_lshl_add_u64 v[0:1], s[92:93], 0, v[6:7]
	v_lshl_add_u64 v[76:77], v[10:11], 0, v[4:5]
	v_lshl_add_u64 v[4:5], s[92:93], 0, v[12:13]
	v_lshl_add_u64 v[82:83], v[0:1], 0, s[14:15]
	v_lshl_add_u64 v[0:1], s[92:93], 0, v[2:3]
	v_add_u32_e32 v108, 0x3000, v104
	v_add_u32_e32 v109, 0x6000, v104
	v_add_u32_e32 v110, 0x9000, v104
	s_mov_b32 s41, -1
	s_mov_b32 s29, 1
	v_mul_u32_u24_e32 v118, 0x84, v111
	v_or_b32_e32 v107, 8, v111
	v_or_b32_e32 v105, 16, v111
	s_waitcnt lgkmcnt(3)
	v_or_b32_e32 v47, 24, v111
	v_lshl_add_u64 v[54:55], v[12:13], 0, s[18:19]
	v_lshl_add_u64 v[60:61], v[2:3], 0, s[18:19]
	v_lshl_add_u64 v[66:67], v[6:7], 0, s[18:19]
	v_lshl_add_u64 v[78:79], v[4:5], 0, s[14:15]
	v_lshl_add_u64 v[84:85], v[0:1], 0, s[14:15]
	s_mov_b64 s[16:17], 0
	s_movk_i32 s6, 0x7fff
	s_mov_b32 s31, 0xffff0000
	v_lshlrev_b32_e32 v86, 2, v8
	s_mov_b32 s34, 0x8b69000
	s_mov_b32 s35, 0x8b6a000
	s_mov_b32 s38, 0x8b67000
	s_mov_b32 s39, 0x8b68000
	s_mov_b64 s[18:19], 0x20000
	s_mov_b64 s[20:21], 0x34800
	v_mov_b32_e32 v135, 1
	s_mov_b32 s40, s30
	v_mov_b32_e32 v0, v45
	v_mov_b32_e32 v1, v45
	v_mov_b32_e32 v2, v45
	v_mov_b32_e32 v3, v45
	v_mov_b32_e32 v4, v45
	v_mov_b32_e32 v5, v45
	v_mov_b32_e32 v6, v45
	v_mov_b32_e32 v7, v45
	v_mov_b32_e32 v8, v45
	v_mov_b32_e32 v9, v45
	v_mov_b32_e32 v10, v45
	v_mov_b32_e32 v11, v45
	v_mov_b32_e32 v12, v45
	v_mov_b32_e32 v13, v45
	v_mov_b32_e32 v14, v45
	v_mov_b32_e32 v15, v45
	v_mov_b32_e32 v16, v45
	v_mov_b32_e32 v17, v45
	v_mov_b32_e32 v18, v45
	v_mov_b32_e32 v19, v45
	v_mov_b32_e32 v20, v45
	v_mov_b32_e32 v21, v45
	v_mov_b32_e32 v22, v45
	v_mov_b32_e32 v23, v45
	v_mov_b32_e32 v24, v45
	v_mov_b32_e32 v25, v45
	v_mov_b32_e32 v26, v45
	v_mov_b32_e32 v27, v45
	v_mov_b32_e32 v28, v45
	v_mov_b32_e32 v29, v45
	v_mov_b32_e32 v30, v45
	v_mov_b32_e32 v31, v45
	s_add_u32 s34, s94, 0x8b685c0
	s_addc_u32 s35, s95, 0
	s_add_u32 s38, s94, 0x8b69800
	s_addc_u32 s39, s95, 0
	s_waitcnt vmcnt(31)
	global_load_dword v170, v56, s[34:35] offset:2624
	global_load_dword v171, v56, s[38:39]
	global_load_dword v172, v56, s[38:39] offset:2048
	global_load_dword v173, v56, s[34:35] offset:-4096
	global_load_dword v174, v56, s[34:35] offset:-2048
	global_load_dword v177, v56, s[34:35]
	global_load_dwordx2 v[202:203], v52, s[94:95]
	global_load_dword v178, v54, s[94:95]
	global_load_dword v186, v62, s[34:35] offset:2624
	global_load_dword v179, v62, s[38:39]
	global_load_dword v187, v62, s[38:39] offset:2048
	global_load_dword v180, v62, s[34:35] offset:-4096
	global_load_dword v181, v62, s[34:35] offset:-2048
	global_load_dword v182, v62, s[34:35]
	global_load_dwordx2 v[204:205], v58, s[94:95]
	global_load_dword v183, v60, s[94:95]
	global_load_dword v191, v68, s[34:35] offset:2624
	global_load_dword v184, v68, s[38:39]
	global_load_dword v192, v68, s[38:39] offset:2048
	global_load_dword v185, v68, s[34:35] offset:-4096
	global_load_dword v188, v68, s[34:35] offset:-2048
	global_load_dword v189, v68, s[34:35]
	global_load_dwordx2 v[206:207], v64, s[94:95]
	global_load_dword v190, v66, s[94:95]
	global_load_dword v198, v76, s[34:35] offset:2624
	global_load_dword v194, v76, s[38:39]
	global_load_dword v199, v76, s[38:39] offset:2048
	global_load_dword v195, v76, s[34:35] offset:-4096
	global_load_dword v196, v76, s[34:35] offset:-2048
	global_load_dword v197, v76, s[34:35]
	global_load_dwordx2 v[208:209], v70, s[94:95]
	global_load_dword v200, v72, s[94:95]
	v_lshl_add_u64 v[52:53], v[52:53], 0, s[18:19]
	v_lshl_add_u64 v[54:55], v[54:55], 0, s[14:15]
	v_lshl_add_u64 v[56:57], v[56:57], 0, s[20:21]
	v_lshl_add_u64 v[58:59], v[58:59], 0, s[18:19]
	v_lshl_add_u64 v[60:61], v[60:61], 0, s[14:15]
	v_lshl_add_u64 v[62:63], v[62:63], 0, s[20:21]
	v_lshl_add_u64 v[64:65], v[64:65], 0, s[18:19]
	v_lshl_add_u64 v[66:67], v[66:67], 0, s[14:15]
	v_lshl_add_u64 v[68:69], v[68:69], 0, s[20:21]
	v_lshl_add_u64 v[70:71], v[70:71], 0, s[18:19]
	v_lshl_add_u64 v[72:73], v[72:73], 0, s[14:15]
	v_lshl_add_u64 v[76:77], v[76:77], 0, s[20:21]
	s_waitcnt vmcnt(32)
	s_waitcnt lgkmcnt(0)
	s_barrier
	s_branch .LBB0_952

.LBB0_961:
	v_add_u32_e32 v44, v117, v118
	v_add_u32_e32 v87, 0x420, v44
	s_waitcnt vmcnt(43)
	ds_write2_b32 v44, v0, v1 offset1:1
	ds_write2_b32 v44, v2, v3 offset0:2 offset1:3
	s_waitcnt vmcnt(42)
	ds_write2_b32 v87, v4, v5 offset1:1
	v_add_u32_e32 v87, 0x428, v44
	ds_write2_b32 v87, v6, v7 offset1:1
	v_add_u32_e32 v87, 0x840, v44
	s_waitcnt vmcnt(41)
	ds_write2_b32 v87, v8, v9 offset1:1
	v_add_u32_e32 v87, 0x848, v44
	ds_write2_b32 v87, v10, v11 offset1:1
	v_add_u32_e32 v87, 0xc60, v44
	s_waitcnt vmcnt(40)
	ds_write2_b32 v87, v12, v13 offset1:1
	v_add_u32_e32 v87, 0xc68, v44
	ds_write2_b32 v87, v14, v15 offset1:1
	v_add_u32_e32 v87, 0x1080, v44
	s_waitcnt vmcnt(39)
	ds_write2_b32 v87, v16, v17 offset1:1
	v_add_u32_e32 v87, 0x1088, v44
	ds_write2_b32 v87, v18, v19 offset1:1
	v_add_u32_e32 v87, 0x14a0, v44
	s_waitcnt vmcnt(38)
	ds_write2_b32 v87, v20, v21 offset1:1
	v_add_u32_e32 v87, 0x14a8, v44
	ds_write2_b32 v87, v22, v23 offset1:1
	v_add_u32_e32 v87, 0x18c0, v44
	s_waitcnt vmcnt(37)
	ds_write2_b32 v87, v24, v25 offset1:1
	v_add_u32_e32 v87, 0x18c8, v44
	s_ff1_i32_b32 s5, s43
	ds_write2_b32 v87, v26, v27 offset1:1
	v_add_u32_e32 v87, 0x1ce0, v44
	v_add_u32_e32 v44, 0x1ce8, v44
	s_lshr_b32 s5, s41, s5
	s_waitcnt vmcnt(36)
	ds_write2_b32 v87, v28, v29 offset1:1
	ds_write2_b32 v44, v30, v31 offset1:1
	s_and_b32 s5, s5, 0xffff
	s_waitcnt lgkmcnt(0)
	s_mul_i32 s42, s43, s5
	ds_read2_b32 v[94:95], v106 offset1:8
	s_sub_i32 s41, s41, s42
	ds_read2_b32 v[98:99], v106 offset0:33 offset1:41
	s_lshl_b32 s41, s41, 5
	s_lshl_b32 s5, s5, 7
	s_add_u32 s22, s22, s5
	ds_read2_b32 v[144:145], v106 offset0:66 offset1:74
	s_addc_u32 s23, s23, 0
	v_lshlrev_b32_e32 v44, 1, v46
	ds_read2_b32 v[146:147], v106 offset0:99 offset1:107
	v_lshl_add_u64 v[96:97], s[22:23], 0, v[44:45]
	s_waitcnt lgkmcnt(2)
	ds_read2_b32 v[148:149], v106 offset0:132 offset1:140
	v_cvt_pk_bf16_f32 v87, v94, v98
	ds_read2_b32 v[150:151], v106 offset0:165 offset1:173
	v_mov_b32_e32 v90, v87
	s_waitcnt lgkmcnt(2)
	ds_read2_b32 v[152:153], v106 offset0:198 offset1:206
	v_cvt_pk_bf16_f32 v87, v144, v146
	ds_read2_b32 v[154:155], v106 offset0:231 offset1:239
	v_mov_b32_e32 v91, v87
	s_waitcnt lgkmcnt(2)
	v_cvt_pk_bf16_f32 v87, v148, v150
	v_mov_b32_e32 v92, v87
	s_waitcnt lgkmcnt(0)
	v_cvt_pk_bf16_f32 v87, v152, v154
	v_mov_b32_e32 v93, v87
	v_or_b32_e32 v44, s41, v111
	v_mad_i64_i32 v[156:157], s[22:23], s4, v44, 0
	v_lshl_add_u64 v[156:157], v[156:157], 1, v[96:97]
	v_cvt_pk_bf16_f32 v87, v95, v99
	global_store_dwordx4 v[156:157], v[90:93], off
	ds_read2_b32 v[94:95], v106 offset0:16 offset1:24
	s_nop 0
	v_mov_b32_e32 v90, v87
	v_cvt_pk_bf16_f32 v87, v145, v147
	v_mov_b32_e32 v91, v87
	v_cvt_pk_bf16_f32 v87, v149, v151
	v_mov_b32_e32 v92, v87
	v_cvt_pk_bf16_f32 v87, v153, v155
	v_mov_b32_e32 v93, v87
	v_or_b32_e32 v44, s41, v107
	v_mad_i64_i32 v[98:99], s[22:23], s4, v44, 0
	v_lshl_add_u64 v[98:99], v[98:99], 1, v[96:97]
	global_store_dwordx4 v[98:99], v[90:93], off
	ds_read2_b32 v[98:99], v106 offset0:49 offset1:57
	ds_read2_b32 v[144:145], v106 offset0:82 offset1:90
	ds_read2_b32 v[146:147], v106 offset0:115 offset1:123
	s_waitcnt lgkmcnt(2)
	ds_read2_b32 v[148:149], v106 offset0:148 offset1:156
	v_cvt_pk_bf16_f32 v87, v94, v98
	ds_read2_b32 v[150:151], v106 offset0:181 offset1:189
	v_mov_b32_e32 v90, v87
	s_waitcnt lgkmcnt(2)
	ds_read2_b32 v[152:153], v106 offset0:214 offset1:222
	v_cvt_pk_bf16_f32 v87, v144, v146
	ds_read2_b32 v[154:155], v106 offset0:247 offset1:255
	v_mov_b32_e32 v91, v87
	s_waitcnt lgkmcnt(2)
	v_cvt_pk_bf16_f32 v87, v148, v150
	v_mov_b32_e32 v92, v87
	s_waitcnt lgkmcnt(0)
	v_cvt_pk_bf16_f32 v87, v152, v154
	v_mov_b32_e32 v93, v87
	v_or_b32_e32 v44, s41, v105
	v_mad_i64_i32 v[156:157], s[22:23], s4, v44, 0
	v_lshl_add_u64 v[156:157], v[156:157], 1, v[96:97]
	v_cvt_pk_bf16_f32 v87, v95, v99
	global_store_dwordx4 v[156:157], v[90:93], off
	s_nop 1
	v_mov_b32_e32 v90, v87
	v_cvt_pk_bf16_f32 v87, v145, v147
	v_mov_b32_e32 v91, v87
	v_cvt_pk_bf16_f32 v87, v149, v151
	v_mov_b32_e32 v92, v87
	v_cvt_pk_bf16_f32 v87, v153, v155
	v_mov_b32_e32 v93, v87
	v_or_b32_e32 v44, s41, v47
	v_mad_i64_i32 v[94:95], s[4:5], s4, v44, 0
	v_lshl_add_u64 v[94:95], v[94:95], 1, v[96:97]
	global_store_dwordx4 v[94:95], v[90:93], off
	s_waitcnt lgkmcnt(0)

.LBB0_970:
	s_lshr_b32 s23, s22, 5
	v_cvt_f32_u32_e32 v0, s23
	s_sub_i32 s44, 0, s23
	s_abs_i32 s43, s41
	s_ashr_i32 s42, s41, 31
	v_rcp_iflag_f32_e32 v0, v0
	v_mov_b32_e32 v87, v45
	v_mul_f32_e32 v0, 0x4f7ffffe, v0
	v_cvt_u32_f32_e32 v0, v0
	s_nop 0
	v_readfirstlane_b32 s45, v0
	s_mul_i32 s44, s44, s45
	s_mul_hi_u32 s44, s45, s44
	s_add_i32 s45, s45, s44
	s_mul_hi_u32 s44, s43, s45
	s_mul_i32 s45, s44, s23
	s_sub_i32 s43, s43, s45
	s_add_i32 s46, s44, 1
	s_sub_i32 s45, s43, s23
	s_cmp_ge_u32 s43, s23
	s_cselect_b32 s44, s46, s44
	s_cselect_b32 s43, s45, s43
	s_add_i32 s45, s44, 1
	s_cmp_ge_u32 s43, s23
	s_cselect_b32 s43, s45, s44
	s_xor_b32 s43, s43, s42
	s_sub_i32 s42, s43, s42
	s_mul_i32 s23, s42, s23
	v_lshl_or_b32 v28, s42, 6, v111
	s_sub_i32 s23, s41, s23
	v_mad_i64_i32 v[0:1], s[42:43], v28, s22, 0
	s_lshl_b32 s42, s23, 5
	s_ashr_i32 s43, s42, 31
	s_lshl_b64 s[42:43], s[42:43], 2
	s_add_u32 s4, s4, s42
	s_addc_u32 s5, s5, s43
	v_or_b32_e32 v2, 8, v28
	v_or_b32_e32 v8, 16, v28
	v_or_b32_e32 v10, 24, v28
	v_or_b32_e32 v16, 32, v28
	v_or_b32_e32 v18, 40, v28
	v_or_b32_e32 v26, 48, v28
	v_or_b32_e32 v28, 56, v28
	v_lshl_add_u64 v[24:25], s[4:5], 0, v[86:87]
	v_mad_i64_i32 v[2:3], s[4:5], v2, s22, 0
	v_mad_i64_i32 v[8:9], s[4:5], v8, s22, 0
	v_mad_i64_i32 v[10:11], s[4:5], v10, s22, 0
	v_mad_i64_i32 v[16:17], s[4:5], v16, s22, 0
	v_mad_i64_i32 v[18:19], s[4:5], v18, s22, 0
	v_mad_i64_i32 v[26:27], s[4:5], v26, s22, 0
	v_mad_i64_i32 v[28:29], s[4:5], v28, s22, 0
	v_lshl_add_u64 v[0:1], v[0:1], 2, v[24:25]
	v_lshl_add_u64 v[4:5], v[2:3], 2, v[24:25]
	v_lshl_add_u64 v[8:9], v[8:9], 2, v[24:25]
	v_lshl_add_u64 v[12:13], v[10:11], 2, v[24:25]
	v_lshl_add_u64 v[16:17], v[16:17], 2, v[24:25]
	v_lshl_add_u64 v[20:21], v[18:19], 2, v[24:25]
	v_lshl_add_u64 v[26:27], v[26:27], 2, v[24:25]
	v_lshl_add_u64 v[28:29], v[28:29], 2, v[24:25]
	global_load_dwordx4 v[0:3], v[0:1], off
	s_nop 0
	global_load_dwordx4 v[4:7], v[4:5], off
	s_nop 0
	global_load_dwordx4 v[8:11], v[8:9], off
	s_nop 0
	global_load_dwordx4 v[12:15], v[12:13], off
	s_nop 0
	global_load_dwordx4 v[16:19], v[16:17], off
	s_nop 0
	global_load_dwordx4 v[20:23], v[20:21], off
	s_nop 0
	global_load_dwordx4 v[24:27], v[26:27], off
	s_nop 0
	global_load_dwordx4 v[28:31], v[28:29], off
	s_mov_b32 s41, s40
.LBB0_971:
	s_cmp_eq_u32 s16, 0x7f0000
	s_cbranch_scc1 .LBB0_951
	v_lshlrev_b32_e32 v94, 16, v113
	v_and_b32_e32 v95, 0xffff0000, v113
	v_lshlrev_b32_e32 v96, 16, v116
	v_and_b32_e32 v97, 0xffff0000, v116
	v_pk_add_f32 v[96:97], v[96:97], v[94:95] neg_lo:[0,1] neg_hi:[0,1]
	v_lshlrev_b32_e32 v90, 16, v112
	v_and_b32_e32 v91, 0xffff0000, v112
	v_lshlrev_b32_e32 v92, 16, v115
	v_and_b32_e32 v93, 0xffff0000, v115
	v_pk_fma_f32 v[96:97], v[38:39], v[96:97], v[94:95]
	v_pk_add_f32 v[92:93], v[92:93], v[90:91] neg_lo:[0,1] neg_hi:[0,1]
	v_pk_mul_f32 v[94:95], v[36:37], v[96:97]
	v_pk_fma_f32 v[90:91], v[32:33], v[92:93], v[90:91]
	v_lshlrev_b32_e32 v92, 16, v120
	v_and_b32_e32 v93, 0xffff0000, v120
	v_pk_mul_f32 v[144:145], v[94:95], v[94:95]
	v_lshlrev_b32_e32 v98, 16, v114
	v_add_f32_e32 v44, v144, v145
	v_pk_add_f32 v[144:145], v[92:93], -1.0 op_sel_hi:[1,0]
	v_and_b32_e32 v99, 0xffff0000, v114
	v_pk_fma_f32 v[144:145], v[40:41], v[144:145], 1.0 op_sel_hi:[1,1,0]
	v_add_f32_dpp v44, v44, v44 quad_perm:[1,0,3,2] row_mask:0xf bank_mask:0xf bound_ctrl:1
	v_pk_mul_f32 v[96:97], v[96:97], v[144:145]
	v_lshlrev_b32_e32 v146, 16, v119
	v_pk_mul_f32 v[144:145], v[90:91], v[96:97]
	v_add_f32_dpp v44, v44, v44 quad_perm:[2,3,0,1] row_mask:0xf bank_mask:0xf bound_ctrl:1
	v_mul_f32_e32 v143, v43, v145
	v_fmac_f32_e32 v143, v42, v144
	v_add_f32_dpp v44, v44, v44 row_half_mirror row_mask:0xf bank_mask:0xf bound_ctrl:1
	v_and_b32_e32 v147, 0xffff0000, v119
	v_add_f32_dpp v143, v143, v143 quad_perm:[1,0,3,2] row_mask:0xf bank_mask:0xf bound_ctrl:1
	v_add_f32_dpp v44, v44, v44 row_mirror row_mask:0xf bank_mask:0xf bound_ctrl:1
	ds_bpermute_b32 v87, v102, v44
	v_add_f32_dpp v143, v143, v143 quad_perm:[2,3,0,1] row_mask:0xf bank_mask:0xf bound_ctrl:1
	v_pk_add_f32 v[146:147], v[146:147], v[98:99] neg_lo:[0,1] neg_hi:[0,1]
	s_nop 0
	v_add_f32_dpp v143, v143, v143 row_half_mirror row_mask:0xf bank_mask:0xf bound_ctrl:1
	v_pk_fma_f32 v[98:99], v[34:35], v[146:147], v[98:99]
	s_nop 0
	v_add_f32_dpp v143, v143, v143 row_mirror row_mask:0xf bank_mask:0xf bound_ctrl:1
	ds_bpermute_b32 v144, v102, v143
	s_and_saveexec_b64 s[4:5], s[0:1]
	s_cbranch_execz .LBB0_974
	s_waitcnt lgkmcnt(0)
	v_add_f32_e32 v144, v143, v144
	v_pk_mul_f32 v[144:145], v[98:99], v[144:145] op_sel_hi:[1,0]
	s_nop 0
	v_and_b32_sdwa v146, v144, v135 dst_sel:DWORD dst_unused:UNUSED_PAD src0_sel:WORD_1 src1_sel:DWORD
	v_and_b32_sdwa v143, v145, v135 dst_sel:DWORD dst_unused:UNUSED_PAD src0_sel:WORD_1 src1_sel:DWORD
	v_add3_u32 v144, v144, v146, s6
	v_add3_u32 v143, v145, v143, s6
	v_lshrrev_b32_e32 v144, 16, v144
	v_and_or_b32 v143, v143, s31, v144
	v_lshl_add_u64 v[144:145], v[78:79], 0, s[16:17]
	global_store_dword v[144:145], v143, off
.LBB0_974:
	s_or_b64 exec, exec, s[4:5]
	s_waitcnt lgkmcnt(1)
	v_add_f32_e32 v44, v44, v87
	s_bitcmp1_b32 s29, 0
	v_and_b32_e32 v147, 0xffff0000, v124
	s_waitcnt lgkmcnt(0)
	s_cselect_b32 s4, 0xc000, 0
	s_add_i32 s22, s4, 0
	v_max_f32_e32 v87, 0x179abe15, v44
	v_rsq_f32_e32 v144, v87
	s_nop 0
	v_lshlrev_b32_e32 v44, 2, v101
	v_pk_mul_f32 v[94:95], v[94:95], v[144:145] op_sel_hi:[1,0] neg_lo:[0,1] neg_hi:[0,1]
	v_add3_u32 v87, s22, v104, v44
	v_pk_mul_f32 v[92:93], v[94:95], v[92:93] neg_lo:[1,0] neg_hi:[1,0]
	ds_write2_b64 v87, v[48:49], v[96:97] offset1:32
	ds_write2_b64 v87, v[94:95], v[92:93] offset0:64 offset1:96
	ds_write2_b64 v87, v[90:91], v[98:99] offset0:128 offset1:160
	v_lshlrev_b32_e32 v94, 16, v121
	v_and_b32_e32 v95, 0xffff0000, v121
	v_lshlrev_b32_e32 v96, 16, v123
	v_and_b32_e32 v97, 0xffff0000, v123
	v_pk_add_f32 v[96:97], v[96:97], v[94:95] neg_lo:[0,1] neg_hi:[0,1]
	v_lshlrev_b32_e32 v90, 16, v128
	v_and_b32_e32 v91, 0xffff0000, v128
	v_lshlrev_b32_e32 v92, 16, v122
	v_and_b32_e32 v93, 0xffff0000, v122
	v_pk_fma_f32 v[96:97], v[38:39], v[96:97], v[94:95]
	v_pk_add_f32 v[92:93], v[92:93], v[90:91] neg_lo:[0,1] neg_hi:[0,1]
	v_pk_mul_f32 v[94:95], v[36:37], v[96:97]
	v_pk_fma_f32 v[90:91], v[32:33], v[92:93], v[90:91]
	v_lshlrev_b32_e32 v92, 16, v125
	v_and_b32_e32 v93, 0xffff0000, v125
	v_pk_mul_f32 v[144:145], v[94:95], v[94:95]
	v_lshlrev_b32_e32 v98, 16, v129
	v_add_f32_e32 v87, v144, v145
	v_pk_add_f32 v[144:145], v[92:93], -1.0 op_sel_hi:[1,0]
	v_and_b32_e32 v99, 0xffff0000, v129
	v_pk_fma_f32 v[144:145], v[40:41], v[144:145], 1.0 op_sel_hi:[1,1,0]
	v_add_f32_dpp v87, v87, v87 quad_perm:[1,0,3,2] row_mask:0xf bank_mask:0xf bound_ctrl:1
	v_pk_mul_f32 v[96:97], v[96:97], v[144:145]
	v_lshlrev_b32_e32 v146, 16, v124
	v_pk_mul_f32 v[144:145], v[90:91], v[96:97]
	v_add_f32_dpp v87, v87, v87 quad_perm:[2,3,0,1] row_mask:0xf bank_mask:0xf bound_ctrl:1
	v_mul_f32_e32 v145, v43, v145
	v_fmac_f32_e32 v145, v42, v144
	v_add_f32_dpp v87, v87, v87 row_half_mirror row_mask:0xf bank_mask:0xf bound_ctrl:1
	v_pk_add_f32 v[146:147], v[146:147], v[98:99] neg_lo:[0,1] neg_hi:[0,1]
	v_add_f32_dpp v144, v145, v145 quad_perm:[1,0,3,2] row_mask:0xf bank_mask:0xf bound_ctrl:1
	v_add_f32_dpp v87, v87, v87 row_mirror row_mask:0xf bank_mask:0xf bound_ctrl:1
	ds_bpermute_b32 v143, v102, v87
	v_add_f32_dpp v144, v144, v144 quad_perm:[2,3,0,1] row_mask:0xf bank_mask:0xf bound_ctrl:1
	v_pk_fma_f32 v[98:99], v[34:35], v[146:147], v[98:99]
	s_nop 0
	v_add_f32_dpp v144, v144, v144 row_half_mirror row_mask:0xf bank_mask:0xf bound_ctrl:1
	s_nop 1
	v_add_f32_dpp v144, v144, v144 row_mirror row_mask:0xf bank_mask:0xf bound_ctrl:1
	ds_bpermute_b32 v145, v102, v144
	s_and_saveexec_b64 s[4:5], s[0:1]
	s_cbranch_execz .LBB0_976
	s_waitcnt lgkmcnt(0)
	v_add_f32_e32 v144, v144, v145
	v_pk_mul_f32 v[144:145], v[98:99], v[144:145] op_sel_hi:[1,0]
	s_nop 0
	v_and_b32_sdwa v147, v144, v135 dst_sel:DWORD dst_unused:UNUSED_PAD src0_sel:WORD_1 src1_sel:DWORD
	v_and_b32_sdwa v146, v145, v135 dst_sel:DWORD dst_unused:UNUSED_PAD src0_sel:WORD_1 src1_sel:DWORD
	v_add3_u32 v144, v144, v147, s6
	v_add3_u32 v145, v145, v146, s6
	v_lshrrev_b32_e32 v144, 16, v144
	v_and_or_b32 v146, v145, s31, v144
	v_lshl_add_u64 v[144:145], v[84:85], 0, s[16:17]
	global_store_dword v[144:145], v146, off
.LBB0_976:
	s_or_b64 exec, exec, s[4:5]
	s_waitcnt lgkmcnt(1)
	v_add_f32_e32 v87, v87, v143
	s_waitcnt lgkmcnt(0)
	v_max_f32_e32 v143, 0x179abe15, v87
	v_rsq_f32_e32 v144, v143
	s_nop 0
	v_pk_mul_f32 v[94:95], v[94:95], v[144:145] op_sel_hi:[1,0] neg_lo:[0,1] neg_hi:[0,1]
	v_add3_u32 v87, s22, v108, v44
	v_pk_mul_f32 v[92:93], v[94:95], v[92:93] neg_lo:[1,0] neg_hi:[1,0]
	ds_write2_b64 v87, v[50:51], v[96:97] offset1:32
	ds_write2_b64 v87, v[94:95], v[92:93] offset0:64 offset1:96
	ds_write2_b64 v87, v[90:91], v[98:99] offset0:128 offset1:160
	v_lshlrev_b32_e32 v94, 16, v126
	v_and_b32_e32 v95, 0xffff0000, v126
	v_lshlrev_b32_e32 v96, 16, v130
	v_and_b32_e32 v97, 0xffff0000, v130
	v_pk_add_f32 v[96:97], v[96:97], v[94:95] neg_lo:[0,1] neg_hi:[0,1]
	v_lshlrev_b32_e32 v90, 16, v133
	v_and_b32_e32 v91, 0xffff0000, v133
	v_lshlrev_b32_e32 v92, 16, v127
	v_and_b32_e32 v93, 0xffff0000, v127
	v_pk_fma_f32 v[96:97], v[38:39], v[96:97], v[94:95]
	v_pk_add_f32 v[92:93], v[92:93], v[90:91] neg_lo:[0,1] neg_hi:[0,1]
	v_pk_mul_f32 v[94:95], v[36:37], v[96:97]
	v_pk_fma_f32 v[90:91], v[32:33], v[92:93], v[90:91]
	v_lshlrev_b32_e32 v92, 16, v132
	v_and_b32_e32 v93, 0xffff0000, v132
	v_pk_mul_f32 v[144:145], v[94:95], v[94:95]
	v_lshlrev_b32_e32 v98, 16, v134
	v_add_f32_e32 v87, v144, v145
	v_pk_add_f32 v[144:145], v[92:93], -1.0 op_sel_hi:[1,0]
	v_and_b32_e32 v99, 0xffff0000, v134
	v_pk_fma_f32 v[144:145], v[40:41], v[144:145], 1.0 op_sel_hi:[1,1,0]
	v_add_f32_dpp v87, v87, v87 quad_perm:[1,0,3,2] row_mask:0xf bank_mask:0xf bound_ctrl:1
	v_pk_mul_f32 v[96:97], v[96:97], v[144:145]
	v_lshlrev_b32_e32 v146, 16, v131
	v_pk_mul_f32 v[144:145], v[90:91], v[96:97]
	v_add_f32_dpp v87, v87, v87 quad_perm:[2,3,0,1] row_mask:0xf bank_mask:0xf bound_ctrl:1
	v_mul_f32_e32 v145, v43, v145
	v_fmac_f32_e32 v145, v42, v144
	v_add_f32_dpp v87, v87, v87 row_half_mirror row_mask:0xf bank_mask:0xf bound_ctrl:1
	v_and_b32_e32 v147, 0xffff0000, v131
	v_add_f32_dpp v144, v145, v145 quad_perm:[1,0,3,2] row_mask:0xf bank_mask:0xf bound_ctrl:1
	v_add_f32_dpp v87, v87, v87 row_mirror row_mask:0xf bank_mask:0xf bound_ctrl:1
	ds_bpermute_b32 v143, v102, v87
	v_add_f32_dpp v144, v144, v144 quad_perm:[2,3,0,1] row_mask:0xf bank_mask:0xf bound_ctrl:1
	v_pk_add_f32 v[146:147], v[146:147], v[98:99] neg_lo:[0,1] neg_hi:[0,1]
	s_nop 0
	v_add_f32_dpp v144, v144, v144 row_half_mirror row_mask:0xf bank_mask:0xf bound_ctrl:1
	v_pk_fma_f32 v[98:99], v[34:35], v[146:147], v[98:99]
	s_nop 0
	v_add_f32_dpp v144, v144, v144 row_mirror row_mask:0xf bank_mask:0xf bound_ctrl:1
	ds_bpermute_b32 v145, v102, v144
	s_and_saveexec_b64 s[4:5], s[0:1]
	s_cbranch_execz .LBB0_978
	s_waitcnt lgkmcnt(0)
	v_add_f32_e32 v144, v144, v145
	v_pk_mul_f32 v[144:145], v[98:99], v[144:145] op_sel_hi:[1,0]
	s_nop 0
	v_and_b32_sdwa v147, v144, v135 dst_sel:DWORD dst_unused:UNUSED_PAD src0_sel:WORD_1 src1_sel:DWORD
	v_and_b32_sdwa v146, v145, v135 dst_sel:DWORD dst_unused:UNUSED_PAD src0_sel:WORD_1 src1_sel:DWORD
	v_add3_u32 v144, v144, v147, s6
	v_add3_u32 v145, v145, v146, s6
	v_lshrrev_b32_e32 v144, 16, v144
	v_and_or_b32 v146, v145, s31, v144
	v_lshl_add_u64 v[144:145], v[82:83], 0, s[16:17]
	global_store_dword v[144:145], v146, off
.LBB0_978:
	s_or_b64 exec, exec, s[4:5]
	s_waitcnt lgkmcnt(1)
	v_add_f32_e32 v87, v87, v143
	s_waitcnt lgkmcnt(0)
	v_max_f32_e32 v143, 0x179abe15, v87
	v_rsq_f32_e32 v144, v143
	s_nop 0
	v_pk_mul_f32 v[94:95], v[94:95], v[144:145] op_sel_hi:[1,0] neg_lo:[0,1] neg_hi:[0,1]
	v_add3_u32 v87, s22, v109, v44
	v_pk_mul_f32 v[92:93], v[94:95], v[92:93] neg_lo:[1,0] neg_hi:[1,0]
	ds_write2_b64 v87, v[74:75], v[96:97] offset1:32
	ds_write2_b64 v87, v[94:95], v[92:93] offset0:64 offset1:96
	ds_write2_b64 v87, v[90:91], v[98:99] offset0:128 offset1:160
	v_lshlrev_b32_e32 v94, 16, v136
	v_and_b32_e32 v95, 0xffff0000, v136
	v_lshlrev_b32_e32 v96, 16, v138
	v_and_b32_e32 v97, 0xffff0000, v138
	v_pk_add_f32 v[96:97], v[96:97], v[94:95] neg_lo:[0,1] neg_hi:[0,1]
	v_lshlrev_b32_e32 v90, 16, v140
	v_and_b32_e32 v91, 0xffff0000, v140
	v_lshlrev_b32_e32 v92, 16, v137
	v_and_b32_e32 v93, 0xffff0000, v137
	v_pk_fma_f32 v[96:97], v[38:39], v[96:97], v[94:95]
	v_pk_add_f32 v[92:93], v[92:93], v[90:91] neg_lo:[0,1] neg_hi:[0,1]
	v_pk_mul_f32 v[94:95], v[36:37], v[96:97]
	v_pk_fma_f32 v[90:91], v[32:33], v[92:93], v[90:91]
	v_lshlrev_b32_e32 v92, 16, v142
	v_and_b32_e32 v93, 0xffff0000, v142
	v_pk_mul_f32 v[144:145], v[94:95], v[94:95]
	v_lshlrev_b32_e32 v98, 16, v141
	v_add_f32_e32 v87, v144, v145
	v_pk_add_f32 v[144:145], v[92:93], -1.0 op_sel_hi:[1,0]
	v_and_b32_e32 v99, 0xffff0000, v141
	v_pk_fma_f32 v[144:145], v[40:41], v[144:145], 1.0 op_sel_hi:[1,1,0]
	v_add_f32_dpp v87, v87, v87 quad_perm:[1,0,3,2] row_mask:0xf bank_mask:0xf bound_ctrl:1
	v_pk_mul_f32 v[96:97], v[96:97], v[144:145]
	v_lshlrev_b32_e32 v146, 16, v139
	v_pk_mul_f32 v[144:145], v[90:91], v[96:97]
	v_add_f32_dpp v87, v87, v87 quad_perm:[2,3,0,1] row_mask:0xf bank_mask:0xf bound_ctrl:1
	v_mul_f32_e32 v145, v43, v145
	v_fmac_f32_e32 v145, v42, v144
	v_add_f32_dpp v87, v87, v87 row_half_mirror row_mask:0xf bank_mask:0xf bound_ctrl:1
	v_and_b32_e32 v147, 0xffff0000, v139
	v_add_f32_dpp v144, v145, v145 quad_perm:[1,0,3,2] row_mask:0xf bank_mask:0xf bound_ctrl:1
	v_add_f32_dpp v87, v87, v87 row_mirror row_mask:0xf bank_mask:0xf bound_ctrl:1
	ds_bpermute_b32 v143, v102, v87
	v_add_f32_dpp v144, v144, v144 quad_perm:[2,3,0,1] row_mask:0xf bank_mask:0xf bound_ctrl:1
	v_pk_add_f32 v[146:147], v[146:147], v[98:99] neg_lo:[0,1] neg_hi:[0,1]
	s_nop 0
	v_add_f32_dpp v144, v144, v144 row_half_mirror row_mask:0xf bank_mask:0xf bound_ctrl:1
	v_pk_fma_f32 v[98:99], v[34:35], v[146:147], v[98:99]
	s_nop 0
	v_add_f32_dpp v144, v144, v144 row_mirror row_mask:0xf bank_mask:0xf bound_ctrl:1
	ds_bpermute_b32 v145, v102, v144
	s_and_saveexec_b64 s[4:5], s[0:1]
	s_cbranch_execz .LBB0_980
	s_waitcnt lgkmcnt(0)
	v_add_f32_e32 v144, v144, v145
	v_pk_mul_f32 v[144:145], v[98:99], v[144:145] op_sel_hi:[1,0]
	s_nop 0
	v_and_b32_sdwa v147, v144, v135 dst_sel:DWORD dst_unused:UNUSED_PAD src0_sel:WORD_1 src1_sel:DWORD
	v_and_b32_sdwa v146, v145, v135 dst_sel:DWORD dst_unused:UNUSED_PAD src0_sel:WORD_1 src1_sel:DWORD
	v_add3_u32 v144, v144, v147, s6
	v_add3_u32 v145, v145, v146, s6
	v_lshrrev_b32_e32 v144, 16, v144
	v_and_or_b32 v146, v145, s31, v144
	v_lshl_add_u64 v[144:145], v[80:81], 0, s[16:17]
	global_store_dword v[144:145], v146, off
.LBB0_980:
	s_or_b64 exec, exec, s[4:5]
	s_waitcnt lgkmcnt(1)
	v_add_f32_e32 v87, v87, v143
	v_add3_u32 v44, s22, v110, v44
	ds_write2_b64 v44, v[88:89], v[96:97] offset1:32
	ds_write2_b64 v44, v[90:91], v[98:99] offset0:128 offset1:160
	s_waitcnt lgkmcnt(2)
	s_add_i32 s4, s29, -1
	s_cmpk_lt_u32 s4, 0x7e
	v_max_f32_e32 v143, 0x179abe15, v87
	v_rsq_f32_e32 v144, v143
	s_nop 0
	v_pk_mul_f32 v[94:95], v[94:95], v[144:145] op_sel_hi:[1,0] neg_lo:[0,1] neg_hi:[0,1]
	s_nop 0
	v_pk_mul_f32 v[92:93], v[94:95], v[92:93] neg_lo:[1,0] neg_hi:[1,0]
	ds_write2_b64 v44, v[94:95], v[92:93] offset0:64 offset1:96
	s_cbranch_scc0 .LBB0_951
	s_cmp_lt_i32 s41, 0
	s_cbranch_scc1 .Lprep_w4
	s_waitcnt vmcnt(12)
	s_branch .Lprep_cp

.Lprep_cp:
	v_mov_b64_e32 v[112:113], v[170:171]
	v_mov_b64_e32 v[114:115], v[172:173]
	v_mov_b64_e32 v[120:121], v[178:179]
	v_mov_b64_e32 v[122:123], v[180:181]
	v_mov_b64_e32 v[124:125], v[182:183]
	v_mov_b64_e32 v[126:127], v[184:185]
	v_mov_b64_e32 v[128:129], v[186:187]
	v_mov_b64_e32 v[130:131], v[188:189]
	v_mov_b64_e32 v[132:133], v[190:191]
	v_mov_b64_e32 v[136:137], v[194:195]
	v_mov_b64_e32 v[138:139], v[196:197]
	v_mov_b64_e32 v[140:141], v[198:199]
	v_mov_b32_e32 v116, v174
	v_mov_b32_e32 v119, v177
	v_mov_b32_e32 v134, v192
	v_mov_b32_e32 v142, v200
	v_mov_b64_e32 v[48:49], v[202:203]
	v_mov_b64_e32 v[50:51], v[204:205]
	v_mov_b64_e32 v[74:75], v[206:207]
	v_mov_b64_e32 v[88:89], v[208:209]
	global_load_dword v170, v56, s[34:35] offset:2624
	global_load_dword v171, v56, s[38:39]
	global_load_dword v172, v56, s[38:39] offset:2048
	global_load_dword v173, v56, s[34:35] offset:-4096
	global_load_dword v174, v56, s[34:35] offset:-2048
	global_load_dword v177, v56, s[34:35]
	global_load_dwordx2 v[202:203], v52, s[94:95]
	global_load_dword v178, v54, s[94:95]
	global_load_dword v186, v62, s[34:35] offset:2624
	global_load_dword v179, v62, s[38:39]
	global_load_dword v187, v62, s[38:39] offset:2048
	global_load_dword v180, v62, s[34:35] offset:-4096
	global_load_dword v181, v62, s[34:35] offset:-2048
	global_load_dword v182, v62, s[34:35]
	global_load_dwordx2 v[204:205], v58, s[94:95]
	global_load_dword v183, v60, s[94:95]
	global_load_dword v191, v68, s[34:35] offset:2624
	global_load_dword v184, v68, s[38:39]
	global_load_dword v192, v68, s[38:39] offset:2048
	global_load_dword v185, v68, s[34:35] offset:-4096
	global_load_dword v188, v68, s[34:35] offset:-2048
	global_load_dword v189, v68, s[34:35]
	global_load_dwordx2 v[206:207], v64, s[94:95]
	global_load_dword v190, v66, s[94:95]
	global_load_dword v198, v76, s[34:35] offset:2624
	global_load_dword v194, v76, s[38:39]
	global_load_dword v199, v76, s[38:39] offset:2048
	global_load_dword v195, v76, s[34:35] offset:-4096
	global_load_dword v196, v76, s[34:35] offset:-2048
	global_load_dword v197, v76, s[34:35]
	global_load_dwordx2 v[208:209], v70, s[94:95]
	global_load_dword v200, v72, s[94:95]
	s_branch .LBB0_951
